# EpiGate: non-temporal hint on the read-once branch-projection (P) loads so the gated-merge read-modify-write lines stay in L2
# speedup vs baseline: 1.0073x; 1.0073x over previous
;     __device__ __forceinline__ void operator()(const f32x4 (&acc)[2][2][4][2], const Unit& u, int wr, int wc, int fr, int fq) const {
;         const int j = u.pn >> 2, ct = u.pn & 3;
;         const int row0 = u.pm * BM + wr * 64 + fr, colg = u.pn * BM + wc * 32 + 8 * fq, colm = ct * BM + wc * 32 + 8 * fq;
;         f32x4 bv[2][2];
; #pragma unroll
;         for (int bj = 0; bj < 2; ++bj)
; #pragma unroll
;             for (int n = 0; n < 2; ++n) bv[bj][n] = *(const f32x4*)(bg + colg + bj * HALF + 4 * n);
; #pragma unroll
;         for (int ai = 0; ai < 2; ++ai)
; #pragma unroll
;             for (int m2 = 0; m2 < 2; ++m2) {
;                 u32x4 pvv[2][2], ovv[2][2];
; #pragma unroll
;                 for (int mm = 0; mm < 2; ++mm) { const size_t row = (size_t)(row0 + ai * HALF + (2 * m2 + mm) * 16);
; #pragma unroll
;                     for (int bj = 0; bj < 2; ++bj) { pvv[mm][bj] = *(const u32x4*)(P + row * 4096 + colg + bj * HALF);
;                         if (j > 0) ovv[mm][bj] = *(const u32x4*)(mixed + row * 1024 + colm + bj * HALF); else ovv[mm][bj] = (u32x4){0u, 0u, 0u, 0u}; } }
; #pragma unroll
;                 for (int mm = 0; mm < 2; ++mm) { const int m = 2 * m2 + mm; const size_t row = (size_t)(row0 + ai * HALF + m * 16);
; #pragma unroll
;                     for (int bj = 0; bj < 2; ++bj) {
;                         const u32x4 pv = pvv[mm][bj], ov = ovv[mm][bj];
;                         bf16_t* mp = mixed + row * 1024 + colm + bj * HALF;
;                         const f32x4 a0 = acc[ai][bj][m][0] + bv[bj][0], a1 = acc[ai][bj][m][1] + bv[bj][1];
;                         float r[8];
;                         r[0] = sigmoidf_(a0[0]) * bflo(pv.x); r[1] = sigmoidf_(a0[1]) * bfhi(pv.x); r[2] = sigmoidf_(a0[2]) * bflo(pv.y); r[3] = sigmoidf_(a0[3]) * bfhi(pv.y);
;                         r[4] = sigmoidf_(a1[0]) * bflo(pv.z); r[5] = sigmoidf_(a1[1]) * bfhi(pv.z); r[6] = sigmoidf_(a1[2]) * bflo(pv.w); r[7] = sigmoidf_(a1[3]) * bfhi(pv.w);
;                         r[0] += bflo(ov.x); r[1] += bfhi(ov.x); r[2] += bflo(ov.y); r[3] += bfhi(ov.y); r[4] += bflo(ov.z); r[5] += bfhi(ov.z); r[6] += bflo(ov.w); r[7] += bfhi(ov.w);
;                         u32x4 w; w.x = cvt_pk_bf16(r[0], r[1]); w.y = cvt_pk_bf16(r[2], r[3]); w.z = cvt_pk_bf16(r[4], r[5]); w.w = cvt_pk_bf16(r[6], r[7]);
;                         *(u32x4*)mp = w; } }
.LBB0_901:
	s_lshl_b32 s13, s67, 8
	v_or_b32_e32 v130, s13, v229
	v_ashrrev_i32_e32 v131, 31, v130
	v_lshl_add_u32 v206, s71, 8, v183
	v_lshl_add_u64 v[28:29], v[130:131], 2, s[8:9]
	v_ashrrev_i32_e32 v207, 31, v206
	global_load_dwordx4 v[32:35], v[28:29], off offset:16
	global_load_dwordx4 v[40:43], v[28:29], off
	global_load_dwordx4 v[24:27], v[28:29], off offset:528
	s_nop 0
	global_load_dwordx4 v[28:31], v[28:29], off offset:512
	v_lshl_add_u64 v[204:205], v[130:131], 1, s[4:5]
	v_lshlrev_b64 v[130:131], 13, v[206:207]
	v_lshl_add_u64 v[130:131], v[204:205], 0, v[130:131]
	global_load_dwordx4 v[170:173], v[130:131], off nt
	s_and_b32 s13, s13, 0x300
	v_or_b32_e32 v64, s13, v229
	v_lshlrev_b32_e32 v64, 1, v64
	s_cmp_gt_i32 s67, 3
	v_lshl_add_u64 v[208:209], s[6:7], 0, v[64:65]
	v_lshlrev_b64 v[212:213], 11, v[206:207]
	s_cselect_b64 s[38:39], -1, 0
	s_cmp_lt_i32 s67, 4
	v_lshl_add_u64 v[132:133], v[208:209], 0, v[212:213]
	v_mov_b32_e32 v154, 0
	v_mov_b32_e32 v174, 0
	v_mov_b32_e32 v175, 0
	v_mov_b32_e32 v176, 0
	v_mov_b32_e32 v177, 0
	s_cbranch_scc1 .LBB0_903
	global_load_dwordx4 v[174:177], v[132:133], off
.LBB0_903:
	global_load_dwordx4 v[158:161], v[130:131], off offset:256 nt
	v_cndmask_b32_e64 v130, 0, 1, s[38:39]
	v_cmp_ne_u32_e64 s[42:43], 1, v130
	s_andn2_b64 vcc, exec, s[38:39]
	v_mov_b32_e32 v155, 0
	v_mov_b32_e32 v156, 0
	v_mov_b32_e32 v157, 0
	s_cbranch_vccnz .LBB0_905
	global_load_dwordx4 v[154:157], v[132:133], off offset:256
.LBB0_905:
	v_or_b32_e32 v130, 16, v206
	v_ashrrev_i32_e32 v131, 31, v130
	v_lshlrev_b64 v[132:133], 13, v[130:131]
	v_lshl_add_u64 v[132:133], v[204:205], 0, v[132:133]
	global_load_dwordx4 v[146:149], v[132:133], off nt
	v_lshlrev_b64 v[210:211], 11, v[130:131]
	v_lshl_add_u64 v[214:215], v[208:209], 0, v[210:211]
	v_mov_b32_e32 v130, 0
	s_and_b64 vcc, exec, s[42:43]
	v_mov_b32_e32 v150, 0
	v_mov_b32_e32 v151, 0
	v_mov_b32_e32 v152, 0
	v_mov_b32_e32 v153, 0
	s_cbranch_vccnz .LBB0_907
	global_load_dwordx4 v[150:153], v[214:215], off
.LBB0_907:
	global_load_dwordx4 v[134:137], v[132:133], off offset:256 nt
	s_and_b64 vcc, exec, s[42:43]
	v_mov_b32_e32 v131, 0
	v_mov_b32_e32 v132, 0
	v_mov_b32_e32 v133, 0
	s_cbranch_vccnz .LBB0_909
	global_load_dwordx4 v[130:133], v[214:215], off offset:256
.LBB0_909:
	v_or_b32_e32 v236, 32, v206
	v_ashrrev_i32_e32 v237, 31, v236
	v_lshlrev_b64 v[236:237], 13, v[236:237]
	v_lshl_add_u64 v[236:237], v[204:205], 0, v[236:237]
	global_load_dwordx4 v[188:191], v[236:237], off nt
	global_load_dwordx4 v[232:235], v[236:237], off offset:256 nt
	v_or_b32_e32 v248, 48, v206
	v_ashrrev_i32_e32 v249, 31, v248
	v_lshlrev_b64 v[248:249], 13, v[248:249]
	v_lshl_add_u64 v[248:249], v[204:205], 0, v[248:249]
	global_load_dwordx4 v[240:243], v[248:249], off nt
	global_load_dwordx4 v[244:247], v[248:249], off offset:256 nt
	s_waitcnt vmcnt(4)
	v_pk_add_f32 v[166:167], v[166:167], v[40:41]
	v_pk_add_f32 v[162:163], v[162:163], v[32:33]
	v_mul_f32_e32 v166, 0xbfb8aa3b, v166
	v_mul_f32_e32 v167, 0xbfb8aa3b, v167
	v_exp_f32_e32 v166, v166
	v_exp_f32_e32 v167, v167
	v_lshl_add_u64 v[178:179], s[6:7], 0, v[212:213]
	v_mul_f32_e32 v162, 0xbfb8aa3b, v162
	v_lshl_add_u64 v[212:213], v[178:179], 0, v[64:65]
	v_pk_add_f32 v[164:165], v[164:165], v[34:35]
	v_exp_f32_e32 v178, v162
	v_mul_f32_e32 v162, 0xbfb8aa3b, v163
	v_exp_f32_e32 v179, v162
	v_mul_f32_e32 v162, 0xbfb8aa3b, v164
	v_mul_f32_e32 v163, 0xbfb8aa3b, v165
	v_pk_add_f32 v[164:165], v[166:167], 1.0 op_sel_hi:[1,0]
	v_pk_add_f32 v[168:169], v[168:169], v[42:43]
	v_mul_f32_e32 v168, 0xbfb8aa3b, v168
	v_mul_f32_e32 v169, 0xbfb8aa3b, v169
	v_exp_f32_e32 v168, v168
	v_rcp_f32_e32 v165, v165
	v_exp_f32_e32 v169, v169
	v_exp_f32_e32 v162, v162
	v_exp_f32_e32 v163, v163
	v_rcp_f32_e32 v164, v164
	v_lshlrev_b32_e32 v166, 16, v170
	v_and_b32_e32 v167, 0xffff0000, v170
	v_lshlrev_b32_e32 v180, 16, v174
	v_and_b32_e32 v181, 0xffff0000, v174
	v_pk_fma_f32 v[164:165], v[164:165], v[166:167], v[180:181]
	v_pk_add_f32 v[166:167], v[168:169], 1.0 op_sel_hi:[1,0]
	v_pk_add_f32 v[162:163], v[162:163], 1.0 op_sel_hi:[1,0]
	v_pk_add_f32 v[142:143], v[142:143], v[28:29]
	v_pk_add_f32 v[138:139], v[138:139], v[24:25]
	v_mul_f32_e32 v142, 0xbfb8aa3b, v142
	v_rcp_f32_e32 v167, v167
	v_mul_f32_e32 v143, 0xbfb8aa3b, v143
	v_exp_f32_e32 v142, v142
	v_exp_f32_e32 v143, v143
	v_rcp_f32_e32 v166, v166
	v_lshlrev_b32_e32 v168, 16, v171
	v_and_b32_e32 v169, 0xffff0000, v171
	v_lshlrev_b32_e32 v170, 16, v175
	v_and_b32_e32 v171, 0xffff0000, v175
	v_pk_fma_f32 v[166:167], v[166:167], v[168:169], v[170:171]
	v_pk_add_f32 v[168:169], v[178:179], 1.0 op_sel_hi:[1,0]
	v_mul_f32_e32 v138, 0xbfb8aa3b, v138
	v_pk_add_f32 v[140:141], v[140:141], v[26:27]
	v_pk_add_f32 v[144:145], v[144:145], v[30:31]
	v_pk_add_f32 v[126:127], v[126:127], v[40:41]
	v_rcp_f32_e32 v169, v169
	v_mul_f32_e32 v144, 0xbfb8aa3b, v144
	v_mul_f32_e32 v145, 0xbfb8aa3b, v145
	v_exp_f32_e32 v144, v144
	v_rcp_f32_e32 v168, v168
	v_lshlrev_b32_e32 v170, 16, v172
	v_and_b32_e32 v171, 0xffff0000, v172
	v_lshlrev_b32_e32 v174, 16, v176
	v_and_b32_e32 v175, 0xffff0000, v176
	v_pk_fma_f32 v[168:169], v[168:169], v[170:171], v[174:175]
	v_exp_f32_e32 v145, v145
	v_mul_f32_e32 v126, 0xbfb8aa3b, v126
	v_mul_f32_e32 v127, 0xbfb8aa3b, v127
	v_rcp_f32_e32 v163, v163
	v_exp_f32_e32 v126, v126
	v_exp_f32_e32 v127, v127
	v_pk_add_f32 v[122:123], v[122:123], v[32:33]
	v_rcp_f32_e32 v162, v162
	v_lshlrev_b32_e32 v170, 16, v173
	v_and_b32_e32 v171, 0xffff0000, v173
	v_lshlrev_b32_e32 v172, 16, v177
	v_and_b32_e32 v173, 0xffff0000, v177
	v_pk_fma_f32 v[170:171], v[162:163], v[170:171], v[172:173]
	v_cvt_pk_bf16_f32 v162, v164, v165
; __device__ __forceinline__ unsigned cvt_pk_bf16(float lo, float hi) { f32x2_t v = {lo, hi}; bf2_t r = __builtin_convertvector(v, bf2_t); return __builtin_bit_cast(unsigned, r); }
; __device__ __forceinline__ float bflo(unsigned u) { return __uint_as_float(u << 16); }
; __device__ __forceinline__ float bfhi(unsigned u) { return __uint_as_float(u & 0xffff0000u); }
; __device__ __forceinline__ float sigmoidf_(float x) { return 1.0f / (1.0f + __expf(-x)); }
;     __device__ __forceinline__ void operator()(const f32x4 (&acc)[2][2][4][2], const Unit& u, int wr, int wc, int fr, int fq) const {
;     ...
;                 for (int mm = 0; mm < 2; ++mm) { const int m = 2 * m2 + mm; const size_t row = (size_t)(row0 + ai * HALF + m * 16);
; #pragma unroll
;                     for (int bj = 0; bj < 2; ++bj) {
;                         const u32x4 pv = pvv[mm][bj], ov = ovv[mm][bj];
;                         bf16_t* mp = mixed + row * 1024 + colm + bj * HALF;
;                         const f32x4 a0 = acc[ai][bj][m][0] + bv[bj][0], a1 = acc[ai][bj][m][1] + bv[bj][1];
;                         float r[8];
;                         r[0] = sigmoidf_(a0[0]) * bflo(pv.x); r[1] = sigmoidf_(a0[1]) * bfhi(pv.x); r[2] = sigmoidf_(a0[2]) * bflo(pv.y); r[3] = sigmoidf_(a0[3]) * bfhi(pv.y);
;                         r[4] = sigmoidf_(a1[0]) * bflo(pv.z); r[5] = sigmoidf_(a1[1]) * bfhi(pv.z); r[6] = sigmoidf_(a1[2]) * bflo(pv.w); r[7] = sigmoidf_(a1[3]) * bfhi(pv.w);
;                         r[0] += bflo(ov.x); r[1] += bfhi(ov.x); r[2] += bflo(ov.y); r[3] += bfhi(ov.y); r[4] += bflo(ov.z); r[5] += bfhi(ov.z); r[6] += bflo(ov.w); r[7] += bfhi(ov.w);
;                         u32x4 w; w.x = cvt_pk_bf16(r[0], r[1]); w.y = cvt_pk_bf16(r[2], r[3]); w.z = cvt_pk_bf16(r[4], r[5]); w.w = cvt_pk_bf16(r[6], r[7]);
;                         *(u32x4*)mp = w; } }
	v_cvt_pk_bf16_f32 v163, v166, v167
	v_cvt_pk_bf16_f32 v164, v168, v169
	v_cvt_pk_bf16_f32 v165, v170, v171
	global_store_dwordx4 v[212:213], v[162:165], off
	v_mul_f32_e32 v122, 0xbfb8aa3b, v122
	v_pk_add_f32 v[124:125], v[124:125], v[34:35]
	v_exp_f32_e32 v162, v138
	v_mul_f32_e32 v138, 0xbfb8aa3b, v139
	v_exp_f32_e32 v163, v138
	v_mul_f32_e32 v138, 0xbfb8aa3b, v140
	v_mul_f32_e32 v139, 0xbfb8aa3b, v141
	v_pk_add_f32 v[140:141], v[142:143], 1.0 op_sel_hi:[1,0]
	v_exp_f32_e32 v138, v138
	v_exp_f32_e32 v139, v139
	v_pk_add_f32 v[128:129], v[128:129], v[42:43]
	v_pk_add_f32 v[118:119], v[118:119], v[28:29]
	v_rcp_f32_e32 v141, v141
	v_pk_add_f32 v[138:139], v[138:139], 1.0 op_sel_hi:[1,0]
	v_mul_f32_e32 v128, 0xbfb8aa3b, v128
	v_mul_f32_e32 v129, 0xbfb8aa3b, v129
	v_rcp_f32_e32 v140, v140
	v_lshlrev_b32_e32 v142, 16, v158
	v_and_b32_e32 v143, 0xffff0000, v158
	v_lshlrev_b32_e32 v164, 16, v154
	v_and_b32_e32 v165, 0xffff0000, v154
	v_pk_fma_f32 v[140:141], v[140:141], v[142:143], v[164:165]
	v_pk_add_f32 v[142:143], v[144:145], 1.0 op_sel_hi:[1,0]
	v_exp_f32_e32 v128, v128
	v_exp_f32_e32 v129, v129
	v_mul_f32_e32 v118, 0xbfb8aa3b, v118
	v_mul_f32_e32 v119, 0xbfb8aa3b, v119
	v_rcp_f32_e32 v143, v143
	v_exp_f32_e32 v118, v118
	v_exp_f32_e32 v119, v119
	v_pk_add_f32 v[114:115], v[114:115], v[24:25]
	v_rcp_f32_e32 v142, v142
	v_lshlrev_b32_e32 v144, 16, v159
	v_and_b32_e32 v145, 0xffff0000, v159
	v_lshlrev_b32_e32 v154, 16, v155
	v_and_b32_e32 v155, 0xffff0000, v155
	v_pk_fma_f32 v[142:143], v[142:143], v[144:145], v[154:155]
	v_pk_add_f32 v[144:145], v[162:163], 1.0 op_sel_hi:[1,0]
	v_mul_f32_e32 v114, 0xbfb8aa3b, v114
	v_pk_add_f32 v[116:117], v[116:117], v[26:27]
	v_pk_add_f32 v[120:121], v[120:121], v[30:31]
	v_rcp_f32_e32 v145, v145
	v_mul_f32_e32 v120, 0xbfb8aa3b, v120
	v_mul_f32_e32 v121, 0xbfb8aa3b, v121
	v_exp_f32_e32 v120, v120
	v_rcp_f32_e32 v144, v144
	v_lshlrev_b32_e32 v154, 16, v160
	v_and_b32_e32 v155, 0xffff0000, v160
	v_lshlrev_b32_e32 v158, 16, v156
	v_and_b32_e32 v159, 0xffff0000, v156
	v_pk_fma_f32 v[144:145], v[144:145], v[154:155], v[158:159]
	v_exp_f32_e32 v121, v121
	v_rcp_f32_e32 v139, v139
	s_nop 0
	v_rcp_f32_e32 v138, v138
	v_lshlrev_b32_e32 v154, 16, v161
	v_and_b32_e32 v155, 0xffff0000, v161
	v_lshlrev_b32_e32 v156, 16, v157
	v_and_b32_e32 v157, 0xffff0000, v157
	v_pk_fma_f32 v[154:155], v[138:139], v[154:155], v[156:157]
	v_cvt_pk_bf16_f32 v138, v140, v141
	v_cvt_pk_bf16_f32 v139, v142, v143
	v_cvt_pk_bf16_f32 v140, v144, v145
	v_cvt_pk_bf16_f32 v141, v154, v155
	global_store_dwordx4 v[212:213], v[138:141], off offset:256
	v_mov_b32_e32 v145, 0
	s_nop 0
	v_exp_f32_e32 v140, v122
	v_mul_f32_e32 v122, 0xbfb8aa3b, v123
	v_exp_f32_e32 v141, v122
	v_mul_f32_e32 v122, 0xbfb8aa3b, v124
	v_mul_f32_e32 v123, 0xbfb8aa3b, v125
	v_pk_add_f32 v[124:125], v[126:127], 1.0 op_sel_hi:[1,0]
	v_exp_f32_e32 v122, v122
	v_exp_f32_e32 v123, v123
	v_lshl_add_u64 v[138:139], s[6:7], 0, v[210:211]
	v_lshl_add_u64 v[138:139], v[138:139], 0, v[64:65]
	v_rcp_f32_e32 v125, v125
	v_pk_add_f32 v[122:123], v[122:123], 1.0 op_sel_hi:[1,0]
	v_rcp_f32_e32 v124, v124
	v_lshlrev_b32_e32 v126, 16, v146
	v_and_b32_e32 v127, 0xffff0000, v146
	v_lshlrev_b32_e32 v142, 16, v150
	v_and_b32_e32 v143, 0xffff0000, v150
	v_pk_fma_f32 v[124:125], v[124:125], v[126:127], v[142:143]
	v_pk_add_f32 v[126:127], v[128:129], 1.0 op_sel_hi:[1,0]
	s_nop 0
	s_nop 0
	v_rcp_f32_e32 v127, v127
	s_nop 0
	v_rcp_f32_e32 v126, v126
	v_lshlrev_b32_e32 v128, 16, v147
	v_and_b32_e32 v129, 0xffff0000, v147
	v_lshlrev_b32_e32 v142, 16, v151
	v_and_b32_e32 v143, 0xffff0000, v151
	v_pk_fma_f32 v[126:127], v[126:127], v[128:129], v[142:143]
	v_pk_add_f32 v[128:129], v[140:141], 1.0 op_sel_hi:[1,0]
	s_nop 0
	s_nop 0
	v_rcp_f32_e32 v129, v129
	s_nop 0
	v_rcp_f32_e32 v128, v128
	v_lshlrev_b32_e32 v140, 16, v148
	v_and_b32_e32 v141, 0xffff0000, v148
	v_lshlrev_b32_e32 v142, 16, v152
	v_and_b32_e32 v143, 0xffff0000, v152
	v_pk_fma_f32 v[128:129], v[128:129], v[140:141], v[142:143]
	s_nop 0
	v_rcp_f32_e32 v123, v123
	s_nop 0
	v_rcp_f32_e32 v122, v122
	v_lshlrev_b32_e32 v140, 16, v149
	v_and_b32_e32 v141, 0xffff0000, v149
	v_lshlrev_b32_e32 v142, 16, v153
	v_and_b32_e32 v143, 0xffff0000, v153
	v_pk_fma_f32 v[140:141], v[122:123], v[140:141], v[142:143]
	v_cvt_pk_bf16_f32 v122, v124, v125
	v_cvt_pk_bf16_f32 v123, v126, v127
	v_cvt_pk_bf16_f32 v124, v128, v129
	v_cvt_pk_bf16_f32 v125, v140, v141
	global_store_dwordx4 v[138:139], v[122:125], off
	v_mov_b32_e32 v142, 0
	v_mov_b32_e32 v143, 0
	v_exp_f32_e32 v122, v114
	v_mul_f32_e32 v114, 0xbfb8aa3b, v115
	v_exp_f32_e32 v123, v114
	v_mul_f32_e32 v114, 0xbfb8aa3b, v116
	v_mul_f32_e32 v115, 0xbfb8aa3b, v117
	v_pk_add_f32 v[116:117], v[118:119], 1.0 op_sel_hi:[1,0]
	v_exp_f32_e32 v114, v114
	v_exp_f32_e32 v115, v115
	v_mov_b32_e32 v144, 0
	v_rcp_f32_e32 v117, v117
	v_pk_add_f32 v[114:115], v[114:115], 1.0 op_sel_hi:[1,0]
	v_rcp_f32_e32 v116, v116
	v_lshlrev_b32_e32 v118, 16, v134
	v_and_b32_e32 v119, 0xffff0000, v134
	v_lshlrev_b32_e32 v124, 16, v130
	v_and_b32_e32 v125, 0xffff0000, v130
	v_pk_fma_f32 v[116:117], v[116:117], v[118:119], v[124:125]
	v_pk_add_f32 v[118:119], v[120:121], 1.0 op_sel_hi:[1,0]
	v_mov_b32_e32 v130, 0
	s_nop 0
	v_rcp_f32_e32 v119, v119
	s_nop 0
	v_rcp_f32_e32 v118, v118
	v_lshlrev_b32_e32 v120, 16, v135
	v_and_b32_e32 v121, 0xffff0000, v135
	v_lshlrev_b32_e32 v124, 16, v131
	v_and_b32_e32 v125, 0xffff0000, v131
	v_pk_fma_f32 v[118:119], v[118:119], v[120:121], v[124:125]
	v_pk_add_f32 v[120:121], v[122:123], 1.0 op_sel_hi:[1,0]
	s_nop 0
	s_nop 0
	v_rcp_f32_e32 v121, v121
	s_nop 0
	v_rcp_f32_e32 v120, v120
	v_lshlrev_b32_e32 v122, 16, v136
	v_and_b32_e32 v123, 0xffff0000, v136
	v_lshlrev_b32_e32 v124, 16, v132
	v_and_b32_e32 v125, 0xffff0000, v132
	v_pk_fma_f32 v[120:121], v[120:121], v[122:123], v[124:125]
	s_nop 0
	v_rcp_f32_e32 v115, v115
	s_nop 0
	v_rcp_f32_e32 v114, v114
	v_lshlrev_b32_e32 v122, 16, v137
	v_and_b32_e32 v123, 0xffff0000, v137
	v_lshlrev_b32_e32 v124, 16, v133
	v_and_b32_e32 v125, 0xffff0000, v133
	v_pk_fma_f32 v[122:123], v[114:115], v[122:123], v[124:125]
	v_cvt_pk_bf16_f32 v114, v116, v117
	v_cvt_pk_bf16_f32 v115, v118, v119
	v_cvt_pk_bf16_f32 v116, v120, v121
	v_cvt_pk_bf16_f32 v117, v122, v123
	global_store_dwordx4 v[138:139], v[114:117], off offset:256
	s_and_b64 vcc, exec, s[42:43]
	s_nop 0
	v_or_b32_e32 v114, 32, v206
	v_ashrrev_i32_e32 v115, 31, v114
	v_lshlrev_b64 v[116:117], 13, v[114:115]
	v_lshl_add_u64 v[116:117], v[204:205], 0, v[116:117]
	s_waitcnt vmcnt(4)
	v_mov_b64_e32 v[138:139], v[188:189]
	v_mov_b64_e32 v[140:141], v[190:191]
	v_lshlrev_b64 v[148:149], 11, v[114:115]
	v_lshl_add_u64 v[114:115], v[208:209], 0, v[148:149]
	s_cbranch_vccnz .LBB0_911
	global_load_dwordx4 v[142:145], v[114:115], off

;     __device__ __forceinline__ void operator()(const f32x4 (&acc)[2][2][4][2], const Unit& u, int wr, int wc, int fr, int fq) const {
;     ...
;                 for (int mm = 0; mm < 2; ++mm) { const size_t row = (size_t)(row0 + ai * HALF + (2 * m2 + mm) * 16);
; #pragma unroll
;                     for (int bj = 0; bj < 2; ++bj) { pvv[mm][bj] = *(const u32x4*)(P + row * 4096 + colg + bj * HALF);
;                         if (j > 0) ovv[mm][bj] = *(const u32x4*)(mixed + row * 1024 + colm + bj * HALF); else ovv[mm][bj] = (u32x4){0u, 0u, 0u, 0u}; } }
.LBB0_917:
	v_add_u32_e32 v236, 0x80, v206
	v_ashrrev_i32_e32 v237, 31, v236
	v_lshlrev_b64 v[236:237], 13, v[236:237]
	v_lshl_add_u64 v[236:237], v[204:205], 0, v[236:237]
	global_load_dwordx4 v[188:191], v[236:237], off nt
	global_load_dwordx4 v[232:235], v[236:237], off offset:256 nt
	v_add_u32_e32 v248, 0x90, v206
	v_ashrrev_i32_e32 v249, 31, v248
	v_lshlrev_b64 v[248:249], 13, v[248:249]
	v_lshl_add_u64 v[248:249], v[204:205], 0, v[248:249]
	global_load_dwordx4 v[240:243], v[248:249], off nt
	global_load_dwordx4 v[244:247], v[248:249], off offset:256 nt
	v_pk_add_f32 v[110:111], v[110:111], v[40:41]
	v_pk_add_f32 v[106:107], v[106:107], v[32:33]
	v_mul_f32_e32 v110, 0xbfb8aa3b, v110
	v_mul_f32_e32 v111, 0xbfb8aa3b, v111
	v_exp_f32_e32 v110, v110
	v_exp_f32_e32 v111, v111
	v_mul_f32_e32 v106, 0xbfb8aa3b, v106
	v_pk_add_f32 v[108:109], v[108:109], v[34:35]
	v_exp_f32_e32 v150, v106
	v_mul_f32_e32 v106, 0xbfb8aa3b, v107
	v_exp_f32_e32 v151, v106
	v_mul_f32_e32 v106, 0xbfb8aa3b, v108
	v_mul_f32_e32 v107, 0xbfb8aa3b, v109
	v_pk_add_f32 v[108:109], v[110:111], 1.0 op_sel_hi:[1,0]
	v_pk_add_f32 v[112:113], v[112:113], v[42:43]
	v_mul_f32_e32 v112, 0xbfb8aa3b, v112
	v_mul_f32_e32 v113, 0xbfb8aa3b, v113
	v_exp_f32_e32 v112, v112
	v_rcp_f32_e32 v109, v109
	v_exp_f32_e32 v113, v113
	v_exp_f32_e32 v106, v106
	v_exp_f32_e32 v107, v107
	v_rcp_f32_e32 v108, v108
	s_waitcnt vmcnt(7)
	v_lshlrev_b32_e32 v110, 16, v138
	v_and_b32_e32 v111, 0xffff0000, v138
	v_lshlrev_b32_e32 v152, 16, v142
	v_and_b32_e32 v153, 0xffff0000, v142
	v_pk_fma_f32 v[108:109], v[108:109], v[110:111], v[152:153]
	v_pk_add_f32 v[110:111], v[112:113], 1.0 op_sel_hi:[1,0]
	v_pk_add_f32 v[106:107], v[106:107], 1.0 op_sel_hi:[1,0]
	v_pk_add_f32 v[102:103], v[102:103], v[28:29]
	v_lshl_add_u64 v[148:149], s[6:7], 0, v[148:149]
	v_mul_f32_e32 v102, 0xbfb8aa3b, v102
	v_rcp_f32_e32 v111, v111
	v_mul_f32_e32 v103, 0xbfb8aa3b, v103
	v_exp_f32_e32 v102, v102
	v_exp_f32_e32 v103, v103
	v_rcp_f32_e32 v110, v110
	v_lshlrev_b32_e32 v112, 16, v139
	v_and_b32_e32 v113, 0xffff0000, v139
	v_lshlrev_b32_e32 v138, 16, v143
	v_and_b32_e32 v139, 0xffff0000, v143
	v_pk_fma_f32 v[110:111], v[110:111], v[112:113], v[138:139]
	v_pk_add_f32 v[112:113], v[150:151], 1.0 op_sel_hi:[1,0]
	v_pk_add_f32 v[98:99], v[98:99], v[24:25]
	v_lshl_add_u64 v[148:149], v[148:149], 0, v[64:65]
	v_mul_f32_e32 v98, 0xbfb8aa3b, v98
	v_pk_add_f32 v[100:101], v[100:101], v[26:27]
	v_rcp_f32_e32 v113, v113
	v_pk_add_f32 v[104:105], v[104:105], v[30:31]
	v_pk_add_f32 v[94:95], v[94:95], v[40:41]
	v_mul_f32_e32 v104, 0xbfb8aa3b, v104
	v_rcp_f32_e32 v112, v112
	v_lshlrev_b32_e32 v138, 16, v140
	v_and_b32_e32 v139, 0xffff0000, v140
	v_lshlrev_b32_e32 v142, 16, v144
	v_and_b32_e32 v143, 0xffff0000, v144
	v_pk_fma_f32 v[112:113], v[112:113], v[138:139], v[142:143]
	v_mul_f32_e32 v105, 0xbfb8aa3b, v105
	v_exp_f32_e32 v104, v104
	v_exp_f32_e32 v105, v105
	v_rcp_f32_e32 v107, v107
	v_mul_f32_e32 v94, 0xbfb8aa3b, v94
	v_mul_f32_e32 v95, 0xbfb8aa3b, v95
	v_exp_f32_e32 v94, v94
	v_rcp_f32_e32 v106, v106
	v_lshlrev_b32_e32 v138, 16, v141
	v_and_b32_e32 v139, 0xffff0000, v141
	v_lshlrev_b32_e32 v140, 16, v145
	v_and_b32_e32 v141, 0xffff0000, v145
	v_pk_fma_f32 v[138:139], v[106:107], v[138:139], v[140:141]
	v_cvt_pk_bf16_f32 v106, v108, v109
	v_cvt_pk_bf16_f32 v107, v110, v111
	v_cvt_pk_bf16_f32 v108, v112, v113
	v_cvt_pk_bf16_f32 v109, v138, v139
	global_store_dwordx4 v[148:149], v[106:109], off
	v_exp_f32_e32 v95, v95
	v_pk_add_f32 v[90:91], v[90:91], v[32:33]
	v_exp_f32_e32 v106, v98
	v_mul_f32_e32 v98, 0xbfb8aa3b, v99
	v_exp_f32_e32 v107, v98
	v_mul_f32_e32 v98, 0xbfb8aa3b, v100
	v_mul_f32_e32 v99, 0xbfb8aa3b, v101
	v_pk_add_f32 v[100:101], v[102:103], 1.0 op_sel_hi:[1,0]
	v_exp_f32_e32 v98, v98
	v_exp_f32_e32 v99, v99
	v_mul_f32_e32 v90, 0xbfb8aa3b, v90
	v_pk_add_f32 v[92:93], v[92:93], v[34:35]
	v_rcp_f32_e32 v101, v101
	v_pk_add_f32 v[98:99], v[98:99], 1.0 op_sel_hi:[1,0]
	v_pk_add_f32 v[96:97], v[96:97], v[42:43]
	v_pk_add_f32 v[86:87], v[86:87], v[28:29]
	v_rcp_f32_e32 v100, v100
	s_waitcnt vmcnt(7)
; __device__ __forceinline__ unsigned cvt_pk_bf16(float lo, float hi) { f32x2_t v = {lo, hi}; bf2_t r = __builtin_convertvector(v, bf2_t); return __builtin_bit_cast(unsigned, r); }
; __device__ __forceinline__ float bflo(unsigned u) { return __uint_as_float(u << 16); }
; __device__ __forceinline__ float bfhi(unsigned u) { return __uint_as_float(u & 0xffff0000u); }
; __device__ __forceinline__ float sigmoidf_(float x) { return 1.0f / (1.0f + __expf(-x)); }
;     __device__ __forceinline__ void operator()(const f32x4 (&acc)[2][2][4][2], const Unit& u, int wr, int wc, int fr, int fq) const {
;     ...
;                 for (int mm = 0; mm < 2; ++mm) { const int m = 2 * m2 + mm; const size_t row = (size_t)(row0 + ai * HALF + m * 16);
; #pragma unroll
;                     for (int bj = 0; bj < 2; ++bj) {
;                         const u32x4 pv = pvv[mm][bj], ov = ovv[mm][bj];
;                         bf16_t* mp = mixed + row * 1024 + colm + bj * HALF;
;                         const f32x4 a0 = acc[ai][bj][m][0] + bv[bj][0], a1 = acc[ai][bj][m][1] + bv[bj][1];
;                         float r[8];
;                         r[0] = sigmoidf_(a0[0]) * bflo(pv.x); r[1] = sigmoidf_(a0[1]) * bfhi(pv.x); r[2] = sigmoidf_(a0[2]) * bflo(pv.y); r[3] = sigmoidf_(a0[3]) * bfhi(pv.y);
;                         r[4] = sigmoidf_(a1[0]) * bflo(pv.z); r[5] = sigmoidf_(a1[1]) * bfhi(pv.z); r[6] = sigmoidf_(a1[2]) * bflo(pv.w); r[7] = sigmoidf_(a1[3]) * bfhi(pv.w);
;                         r[0] += bflo(ov.x); r[1] += bfhi(ov.x); r[2] += bflo(ov.y); r[3] += bfhi(ov.y); r[4] += bflo(ov.z); r[5] += bfhi(ov.z); r[6] += bflo(ov.w); r[7] += bfhi(ov.w);
;                         u32x4 w; w.x = cvt_pk_bf16(r[0], r[1]); w.y = cvt_pk_bf16(r[2], r[3]); w.z = cvt_pk_bf16(r[4], r[5]); w.w = cvt_pk_bf16(r[6], r[7]);
;                         *(u32x4*)mp = w; } }
	v_lshlrev_b32_e32 v102, 16, v134
	v_and_b32_e32 v103, 0xffff0000, v134
	v_lshlrev_b32_e32 v108, 16, v130
	v_and_b32_e32 v109, 0xffff0000, v130
	v_pk_fma_f32 v[100:101], v[100:101], v[102:103], v[108:109]
	v_pk_add_f32 v[102:103], v[104:105], 1.0 op_sel_hi:[1,0]
	v_mul_f32_e32 v96, 0xbfb8aa3b, v96
	v_mul_f32_e32 v97, 0xbfb8aa3b, v97
	v_exp_f32_e32 v96, v96
	v_exp_f32_e32 v97, v97
	v_rcp_f32_e32 v103, v103
	v_mul_f32_e32 v86, 0xbfb8aa3b, v86
	v_mul_f32_e32 v87, 0xbfb8aa3b, v87
	v_exp_f32_e32 v86, v86
	v_rcp_f32_e32 v102, v102
	v_lshlrev_b32_e32 v104, 16, v135
	v_and_b32_e32 v105, 0xffff0000, v135
	v_lshlrev_b32_e32 v108, 16, v131
	v_and_b32_e32 v109, 0xffff0000, v131
	v_pk_fma_f32 v[102:103], v[102:103], v[104:105], v[108:109]
	v_pk_add_f32 v[104:105], v[106:107], 1.0 op_sel_hi:[1,0]
	v_exp_f32_e32 v87, v87
	v_pk_add_f32 v[82:83], v[82:83], v[24:25]
	v_pk_add_f32 v[84:85], v[84:85], v[26:27]
	v_mul_f32_e32 v82, 0xbfb8aa3b, v82
	v_rcp_f32_e32 v105, v105
	v_pk_add_f32 v[88:89], v[88:89], v[30:31]
	v_mov_b32_e32 v111, 0
	v_mul_f32_e32 v88, 0xbfb8aa3b, v88
	v_rcp_f32_e32 v104, v104
	v_lshlrev_b32_e32 v106, 16, v136
	v_and_b32_e32 v107, 0xffff0000, v136
	v_lshlrev_b32_e32 v108, 16, v132
	v_and_b32_e32 v109, 0xffff0000, v132
	v_pk_fma_f32 v[104:105], v[104:105], v[106:107], v[108:109]
	v_mul_f32_e32 v89, 0xbfb8aa3b, v89
	v_exp_f32_e32 v88, v88
	v_exp_f32_e32 v89, v89
	v_rcp_f32_e32 v99, v99
	v_mov_b32_e32 v112, 0
	v_mov_b32_e32 v113, 0
	v_rcp_f32_e32 v98, v98
	v_lshlrev_b32_e32 v106, 16, v137
	v_and_b32_e32 v107, 0xffff0000, v137
	v_lshlrev_b32_e32 v108, 16, v133
	v_and_b32_e32 v109, 0xffff0000, v133
	v_pk_fma_f32 v[106:107], v[98:99], v[106:107], v[108:109]
	v_cvt_pk_bf16_f32 v98, v100, v101
	v_cvt_pk_bf16_f32 v99, v102, v103
	v_cvt_pk_bf16_f32 v100, v104, v105
	v_cvt_pk_bf16_f32 v101, v106, v107
	global_store_dwordx4 v[148:149], v[98:101], off offset:256
	v_mov_b32_e32 v110, 0
	s_nop 0
	v_exp_f32_e32 v100, v90
	v_mul_f32_e32 v90, 0xbfb8aa3b, v91
	v_exp_f32_e32 v101, v90
	v_mul_f32_e32 v90, 0xbfb8aa3b, v92
	v_mul_f32_e32 v91, 0xbfb8aa3b, v93
	v_pk_add_f32 v[92:93], v[94:95], 1.0 op_sel_hi:[1,0]
	v_exp_f32_e32 v90, v90
	v_exp_f32_e32 v91, v91
	v_lshl_add_u64 v[98:99], s[6:7], 0, v[146:147]
	v_lshl_add_u64 v[98:99], v[98:99], 0, v[64:65]
	v_rcp_f32_e32 v93, v93
	v_pk_add_f32 v[90:91], v[90:91], 1.0 op_sel_hi:[1,0]
	v_rcp_f32_e32 v92, v92
	s_waitcnt vmcnt(7)
	v_lshlrev_b32_e32 v94, 16, v122
	v_and_b32_e32 v95, 0xffff0000, v122
	v_lshlrev_b32_e32 v102, 16, v126
	v_and_b32_e32 v103, 0xffff0000, v126
	v_pk_fma_f32 v[92:93], v[92:93], v[94:95], v[102:103]
	v_pk_add_f32 v[94:95], v[96:97], 1.0 op_sel_hi:[1,0]
	s_nop 0
	s_nop 0
	v_rcp_f32_e32 v95, v95
	s_nop 0
	v_rcp_f32_e32 v94, v94
	v_lshlrev_b32_e32 v96, 16, v123
	v_and_b32_e32 v97, 0xffff0000, v123
	v_lshlrev_b32_e32 v102, 16, v127
	v_and_b32_e32 v103, 0xffff0000, v127
	v_pk_fma_f32 v[94:95], v[94:95], v[96:97], v[102:103]
	v_pk_add_f32 v[96:97], v[100:101], 1.0 op_sel_hi:[1,0]
	s_nop 0
	s_nop 0
	v_rcp_f32_e32 v97, v97
	s_nop 0
	v_rcp_f32_e32 v96, v96
	v_lshlrev_b32_e32 v100, 16, v124
	v_and_b32_e32 v101, 0xffff0000, v124
	v_lshlrev_b32_e32 v102, 16, v128
	v_and_b32_e32 v103, 0xffff0000, v128
	v_pk_fma_f32 v[96:97], v[96:97], v[100:101], v[102:103]
	s_nop 0
	v_rcp_f32_e32 v91, v91
	s_nop 0
	v_rcp_f32_e32 v90, v90
	v_lshlrev_b32_e32 v100, 16, v125
	v_and_b32_e32 v101, 0xffff0000, v125
	v_lshlrev_b32_e32 v102, 16, v129
	v_and_b32_e32 v103, 0xffff0000, v129
	v_pk_fma_f32 v[100:101], v[90:91], v[100:101], v[102:103]
	v_cvt_pk_bf16_f32 v90, v92, v93
	v_cvt_pk_bf16_f32 v91, v94, v95
	v_cvt_pk_bf16_f32 v92, v96, v97
	v_cvt_pk_bf16_f32 v93, v100, v101
	global_store_dwordx4 v[98:99], v[90:93], off
	s_nop 1
	v_exp_f32_e32 v90, v82
	v_mul_f32_e32 v82, 0xbfb8aa3b, v83
	v_exp_f32_e32 v91, v82
	v_mul_f32_e32 v82, 0xbfb8aa3b, v84
	v_mul_f32_e32 v83, 0xbfb8aa3b, v85
	v_pk_add_f32 v[84:85], v[86:87], 1.0 op_sel_hi:[1,0]
	v_exp_f32_e32 v82, v82
	v_exp_f32_e32 v83, v83
	v_rcp_f32_e32 v85, v85
	v_pk_add_f32 v[82:83], v[82:83], 1.0 op_sel_hi:[1,0]
	v_rcp_f32_e32 v84, v84
	s_waitcnt vmcnt(7)
	v_lshlrev_b32_e32 v86, 16, v118
	v_and_b32_e32 v87, 0xffff0000, v118
	v_lshlrev_b32_e32 v92, 16, v114
	v_and_b32_e32 v93, 0xffff0000, v114
	v_pk_fma_f32 v[84:85], v[84:85], v[86:87], v[92:93]
	v_pk_add_f32 v[86:87], v[88:89], 1.0 op_sel_hi:[1,0]
	s_nop 0
	s_nop 0
	v_rcp_f32_e32 v87, v87
	s_nop 0
	v_rcp_f32_e32 v86, v86
	v_lshlrev_b32_e32 v88, 16, v119
	v_and_b32_e32 v89, 0xffff0000, v119
	v_lshlrev_b32_e32 v92, 16, v115
	v_and_b32_e32 v93, 0xffff0000, v115
	v_pk_fma_f32 v[86:87], v[86:87], v[88:89], v[92:93]
	v_pk_add_f32 v[88:89], v[90:91], 1.0 op_sel_hi:[1,0]
	s_nop 0
	s_nop 0
	v_rcp_f32_e32 v89, v89
	s_nop 0
	v_rcp_f32_e32 v88, v88
	v_lshlrev_b32_e32 v90, 16, v120
	v_and_b32_e32 v91, 0xffff0000, v120
	v_lshlrev_b32_e32 v92, 16, v116
	v_and_b32_e32 v93, 0xffff0000, v116
	v_pk_fma_f32 v[88:89], v[88:89], v[90:91], v[92:93]
	s_nop 0
	v_rcp_f32_e32 v83, v83
	s_nop 0
	v_rcp_f32_e32 v82, v82
	v_lshlrev_b32_e32 v90, 16, v121
	v_and_b32_e32 v91, 0xffff0000, v121
	v_lshlrev_b32_e32 v92, 16, v117
	v_and_b32_e32 v93, 0xffff0000, v117
	v_pk_fma_f32 v[90:91], v[82:83], v[90:91], v[92:93]
	v_cvt_pk_bf16_f32 v82, v84, v85
	v_cvt_pk_bf16_f32 v83, v86, v87
	v_cvt_pk_bf16_f32 v84, v88, v89
	v_cvt_pk_bf16_f32 v85, v90, v91
	global_store_dwordx4 v[98:99], v[82:85], off offset:256
	v_mov_b32_e32 v98, 0
	s_and_b64 vcc, exec, s[42:43]
	v_add_u32_e32 v82, 0x80, v206
	v_ashrrev_i32_e32 v83, 31, v82
	v_lshlrev_b64 v[84:85], 13, v[82:83]
	v_lshl_add_u64 v[84:85], v[204:205], 0, v[84:85]
	s_waitcnt vmcnt(4)
	v_mov_b64_e32 v[106:107], v[188:189]
	v_mov_b64_e32 v[108:109], v[190:191]
	v_lshlrev_b64 v[116:117], 11, v[82:83]
	v_lshl_add_u64 v[82:83], v[208:209], 0, v[116:117]
	s_cbranch_vccnz .LBB0_919
	global_load_dwordx4 v[110:113], v[82:83], off

;     __device__ __forceinline__ void operator()(const f32x4 (&acc)[2][2][4][2], const Unit& u, int wr, int wc, int fr, int fq) const {
;     ...
;                 for (int mm = 0; mm < 2; ++mm) { const size_t row = (size_t)(row0 + ai * HALF + (2 * m2 + mm) * 16);
; #pragma unroll
;                     for (int bj = 0; bj < 2; ++bj) { pvv[mm][bj] = *(const u32x4*)(P + row * 4096 + colg + bj * HALF);
;                         if (j > 0) ovv[mm][bj] = *(const u32x4*)(mixed + row * 1024 + colm + bj * HALF); else ovv[mm][bj] = (u32x4){0u, 0u, 0u, 0u}; } }
.LBB0_925:
	v_add_u32_e32 v236, 0xa0, v206
	v_ashrrev_i32_e32 v237, 31, v236
	v_lshlrev_b64 v[236:237], 13, v[236:237]
	v_lshl_add_u64 v[236:237], v[204:205], 0, v[236:237]
	global_load_dwordx4 v[188:191], v[236:237], off nt
	global_load_dwordx4 v[232:235], v[236:237], off offset:256 nt
	v_add_u32_e32 v248, 0xb0, v206
	v_ashrrev_i32_e32 v249, 31, v248
	v_lshlrev_b64 v[248:249], 13, v[248:249]
	v_lshl_add_u64 v[248:249], v[204:205], 0, v[248:249]
	global_load_dwordx4 v[240:243], v[248:249], off nt
	global_load_dwordx4 v[244:247], v[248:249], off offset:256 nt
	v_pk_add_f32 v[78:79], v[78:79], v[40:41]
	v_pk_add_f32 v[74:75], v[74:75], v[32:33]
	v_mul_f32_e32 v78, 0xbfb8aa3b, v78
	v_mul_f32_e32 v79, 0xbfb8aa3b, v79
	v_exp_f32_e32 v78, v78
	v_exp_f32_e32 v79, v79
	v_mul_f32_e32 v74, 0xbfb8aa3b, v74
	v_pk_add_f32 v[76:77], v[76:77], v[34:35]
	v_exp_f32_e32 v118, v74
	v_mul_f32_e32 v74, 0xbfb8aa3b, v75
	v_exp_f32_e32 v119, v74
	v_mul_f32_e32 v74, 0xbfb8aa3b, v76
	v_mul_f32_e32 v75, 0xbfb8aa3b, v77
	v_pk_add_f32 v[76:77], v[78:79], 1.0 op_sel_hi:[1,0]
	v_pk_add_f32 v[80:81], v[80:81], v[42:43]
	v_mul_f32_e32 v80, 0xbfb8aa3b, v80
	v_mul_f32_e32 v81, 0xbfb8aa3b, v81
	v_exp_f32_e32 v80, v80
	v_rcp_f32_e32 v77, v77
	v_exp_f32_e32 v81, v81
	v_exp_f32_e32 v74, v74
	v_exp_f32_e32 v75, v75
	v_rcp_f32_e32 v76, v76
	s_waitcnt vmcnt(7)
	v_lshlrev_b32_e32 v78, 16, v106
	v_and_b32_e32 v79, 0xffff0000, v106
	v_lshlrev_b32_e32 v120, 16, v110
	v_and_b32_e32 v121, 0xffff0000, v110
	v_pk_fma_f32 v[76:77], v[76:77], v[78:79], v[120:121]
	v_pk_add_f32 v[78:79], v[80:81], 1.0 op_sel_hi:[1,0]
	v_pk_add_f32 v[74:75], v[74:75], 1.0 op_sel_hi:[1,0]
	v_pk_add_f32 v[70:71], v[70:71], v[28:29]
	v_lshl_add_u64 v[116:117], s[6:7], 0, v[116:117]
	v_mul_f32_e32 v70, 0xbfb8aa3b, v70
	v_rcp_f32_e32 v79, v79
	v_mul_f32_e32 v71, 0xbfb8aa3b, v71
	v_exp_f32_e32 v70, v70
	v_exp_f32_e32 v71, v71
	v_rcp_f32_e32 v78, v78
	v_lshlrev_b32_e32 v80, 16, v107
	v_and_b32_e32 v81, 0xffff0000, v107
	v_lshlrev_b32_e32 v106, 16, v111
	v_and_b32_e32 v107, 0xffff0000, v111
	v_pk_fma_f32 v[78:79], v[78:79], v[80:81], v[106:107]
	v_pk_add_f32 v[80:81], v[118:119], 1.0 op_sel_hi:[1,0]
	v_pk_add_f32 v[66:67], v[66:67], v[24:25]
	v_lshl_add_u64 v[116:117], v[116:117], 0, v[64:65]
	v_mul_f32_e32 v66, 0xbfb8aa3b, v66
	v_pk_add_f32 v[68:69], v[68:69], v[26:27]
	v_rcp_f32_e32 v81, v81
	v_pk_add_f32 v[72:73], v[72:73], v[30:31]
	v_pk_add_f32 v[60:61], v[60:61], v[40:41]
	v_mul_f32_e32 v72, 0xbfb8aa3b, v72
	v_rcp_f32_e32 v80, v80
	v_lshlrev_b32_e32 v106, 16, v108
	v_and_b32_e32 v107, 0xffff0000, v108
	v_lshlrev_b32_e32 v110, 16, v112
	v_and_b32_e32 v111, 0xffff0000, v112
	v_pk_fma_f32 v[80:81], v[80:81], v[106:107], v[110:111]
	v_mul_f32_e32 v73, 0xbfb8aa3b, v73
	v_exp_f32_e32 v72, v72
	v_exp_f32_e32 v73, v73
	v_rcp_f32_e32 v75, v75
	v_mul_f32_e32 v60, 0xbfb8aa3b, v60
	v_mul_f32_e32 v61, 0xbfb8aa3b, v61
	v_exp_f32_e32 v60, v60
	v_rcp_f32_e32 v74, v74
	v_lshlrev_b32_e32 v106, 16, v109
	v_and_b32_e32 v107, 0xffff0000, v109
	v_lshlrev_b32_e32 v108, 16, v113
	v_and_b32_e32 v109, 0xffff0000, v113
	v_pk_fma_f32 v[106:107], v[74:75], v[106:107], v[108:109]
	v_cvt_pk_bf16_f32 v74, v76, v77
	v_cvt_pk_bf16_f32 v75, v78, v79
	v_cvt_pk_bf16_f32 v76, v80, v81
	v_cvt_pk_bf16_f32 v77, v106, v107
	global_store_dwordx4 v[116:117], v[74:77], off
	v_exp_f32_e32 v61, v61
	v_pk_add_f32 v[56:57], v[56:57], v[32:33]
	v_exp_f32_e32 v74, v66
	v_mul_f32_e32 v66, 0xbfb8aa3b, v67
	v_exp_f32_e32 v75, v66
	v_mul_f32_e32 v66, 0xbfb8aa3b, v68
	v_mul_f32_e32 v67, 0xbfb8aa3b, v69
	v_pk_add_f32 v[68:69], v[70:71], 1.0 op_sel_hi:[1,0]
	v_exp_f32_e32 v66, v66
	v_exp_f32_e32 v67, v67
	v_mul_f32_e32 v56, 0xbfb8aa3b, v56
	v_pk_add_f32 v[58:59], v[58:59], v[34:35]
	v_rcp_f32_e32 v69, v69
	v_pk_add_f32 v[66:67], v[66:67], 1.0 op_sel_hi:[1,0]
	v_pk_add_f32 v[62:63], v[62:63], v[42:43]
	v_pk_add_f32 v[52:53], v[52:53], v[28:29]
	v_rcp_f32_e32 v68, v68
	s_waitcnt vmcnt(7)
; __device__ __forceinline__ unsigned cvt_pk_bf16(float lo, float hi) { f32x2_t v = {lo, hi}; bf2_t r = __builtin_convertvector(v, bf2_t); return __builtin_bit_cast(unsigned, r); }
; __device__ __forceinline__ float bflo(unsigned u) { return __uint_as_float(u << 16); }
; __device__ __forceinline__ float bfhi(unsigned u) { return __uint_as_float(u & 0xffff0000u); }
; __device__ __forceinline__ float sigmoidf_(float x) { return 1.0f / (1.0f + __expf(-x)); }
;     __device__ __forceinline__ void operator()(const f32x4 (&acc)[2][2][4][2], const Unit& u, int wr, int wc, int fr, int fq) const {
;     ...
;                 for (int mm = 0; mm < 2; ++mm) { const int m = 2 * m2 + mm; const size_t row = (size_t)(row0 + ai * HALF + m * 16);
; #pragma unroll
;                     for (int bj = 0; bj < 2; ++bj) {
;                         const u32x4 pv = pvv[mm][bj], ov = ovv[mm][bj];
;                         bf16_t* mp = mixed + row * 1024 + colm + bj * HALF;
;                         const f32x4 a0 = acc[ai][bj][m][0] + bv[bj][0], a1 = acc[ai][bj][m][1] + bv[bj][1];
;                         float r[8];
;                         r[0] = sigmoidf_(a0[0]) * bflo(pv.x); r[1] = sigmoidf_(a0[1]) * bfhi(pv.x); r[2] = sigmoidf_(a0[2]) * bflo(pv.y); r[3] = sigmoidf_(a0[3]) * bfhi(pv.y);
;                         r[4] = sigmoidf_(a1[0]) * bflo(pv.z); r[5] = sigmoidf_(a1[1]) * bfhi(pv.z); r[6] = sigmoidf_(a1[2]) * bflo(pv.w); r[7] = sigmoidf_(a1[3]) * bfhi(pv.w);
;                         r[0] += bflo(ov.x); r[1] += bfhi(ov.x); r[2] += bflo(ov.y); r[3] += bfhi(ov.y); r[4] += bflo(ov.z); r[5] += bfhi(ov.z); r[6] += bflo(ov.w); r[7] += bfhi(ov.w);
;                         u32x4 w; w.x = cvt_pk_bf16(r[0], r[1]); w.y = cvt_pk_bf16(r[2], r[3]); w.z = cvt_pk_bf16(r[4], r[5]); w.w = cvt_pk_bf16(r[6], r[7]);
;                         *(u32x4*)mp = w; } }
	v_lshlrev_b32_e32 v70, 16, v102
	v_and_b32_e32 v71, 0xffff0000, v102
	v_lshlrev_b32_e32 v76, 16, v98
	v_and_b32_e32 v77, 0xffff0000, v98
	v_pk_fma_f32 v[68:69], v[68:69], v[70:71], v[76:77]
	v_pk_add_f32 v[70:71], v[72:73], 1.0 op_sel_hi:[1,0]
	v_mul_f32_e32 v62, 0xbfb8aa3b, v62
	v_mul_f32_e32 v63, 0xbfb8aa3b, v63
	v_exp_f32_e32 v62, v62
	v_exp_f32_e32 v63, v63
	v_rcp_f32_e32 v71, v71
	v_mul_f32_e32 v52, 0xbfb8aa3b, v52
	v_mul_f32_e32 v53, 0xbfb8aa3b, v53
	v_exp_f32_e32 v52, v52
	v_rcp_f32_e32 v70, v70
	v_lshlrev_b32_e32 v72, 16, v103
	v_and_b32_e32 v73, 0xffff0000, v103
	v_lshlrev_b32_e32 v76, 16, v99
	v_and_b32_e32 v77, 0xffff0000, v99
	v_pk_fma_f32 v[70:71], v[70:71], v[72:73], v[76:77]
	v_pk_add_f32 v[72:73], v[74:75], 1.0 op_sel_hi:[1,0]
	v_exp_f32_e32 v53, v53
	v_pk_add_f32 v[48:49], v[48:49], v[24:25]
	v_pk_add_f32 v[50:51], v[50:51], v[26:27]
	v_mul_f32_e32 v48, 0xbfb8aa3b, v48
	v_rcp_f32_e32 v73, v73
	v_pk_add_f32 v[54:55], v[54:55], v[30:31]
	v_mov_b32_e32 v79, 0
	v_mul_f32_e32 v54, 0xbfb8aa3b, v54
	v_rcp_f32_e32 v72, v72
	v_lshlrev_b32_e32 v74, 16, v104
	v_and_b32_e32 v75, 0xffff0000, v104
	v_lshlrev_b32_e32 v76, 16, v100
	v_and_b32_e32 v77, 0xffff0000, v100
	v_pk_fma_f32 v[72:73], v[72:73], v[74:75], v[76:77]
	v_mul_f32_e32 v55, 0xbfb8aa3b, v55
	v_exp_f32_e32 v54, v54
	v_exp_f32_e32 v55, v55
	v_rcp_f32_e32 v67, v67
	v_mov_b32_e32 v80, 0
	v_mov_b32_e32 v81, 0
	v_rcp_f32_e32 v66, v66
	v_lshlrev_b32_e32 v74, 16, v105
	v_and_b32_e32 v75, 0xffff0000, v105
	v_lshlrev_b32_e32 v76, 16, v101
	v_and_b32_e32 v77, 0xffff0000, v101
	v_pk_fma_f32 v[74:75], v[66:67], v[74:75], v[76:77]
	v_cvt_pk_bf16_f32 v66, v68, v69
	v_cvt_pk_bf16_f32 v67, v70, v71
	v_cvt_pk_bf16_f32 v68, v72, v73
	v_cvt_pk_bf16_f32 v69, v74, v75
	global_store_dwordx4 v[116:117], v[66:69], off offset:256
	v_mov_b32_e32 v78, 0
	s_nop 0
	v_exp_f32_e32 v68, v56
	v_mul_f32_e32 v56, 0xbfb8aa3b, v57
	v_exp_f32_e32 v69, v56
	v_mul_f32_e32 v56, 0xbfb8aa3b, v58
	v_mul_f32_e32 v57, 0xbfb8aa3b, v59
	v_pk_add_f32 v[58:59], v[60:61], 1.0 op_sel_hi:[1,0]
	v_exp_f32_e32 v56, v56
	v_exp_f32_e32 v57, v57
	v_lshl_add_u64 v[66:67], s[6:7], 0, v[114:115]
	v_lshl_add_u64 v[66:67], v[66:67], 0, v[64:65]
	v_rcp_f32_e32 v59, v59
	v_pk_add_f32 v[56:57], v[56:57], 1.0 op_sel_hi:[1,0]
	v_rcp_f32_e32 v58, v58
	s_waitcnt vmcnt(7)
	v_lshlrev_b32_e32 v60, 16, v90
	v_and_b32_e32 v61, 0xffff0000, v90
	v_lshlrev_b32_e32 v70, 16, v94
	v_and_b32_e32 v71, 0xffff0000, v94
	v_pk_fma_f32 v[58:59], v[58:59], v[60:61], v[70:71]
	v_pk_add_f32 v[60:61], v[62:63], 1.0 op_sel_hi:[1,0]
	s_nop 0
	s_nop 0
	v_rcp_f32_e32 v61, v61
	s_nop 0
	v_rcp_f32_e32 v60, v60
	v_lshlrev_b32_e32 v62, 16, v91
	v_and_b32_e32 v63, 0xffff0000, v91
	v_lshlrev_b32_e32 v70, 16, v95
	v_and_b32_e32 v71, 0xffff0000, v95
	v_pk_fma_f32 v[60:61], v[60:61], v[62:63], v[70:71]
	v_pk_add_f32 v[62:63], v[68:69], 1.0 op_sel_hi:[1,0]
	s_nop 0
	s_nop 0
	v_rcp_f32_e32 v63, v63
	s_nop 0
	v_rcp_f32_e32 v62, v62
	v_lshlrev_b32_e32 v68, 16, v92
	v_and_b32_e32 v69, 0xffff0000, v92
	v_lshlrev_b32_e32 v70, 16, v96
	v_and_b32_e32 v71, 0xffff0000, v96
	v_pk_fma_f32 v[62:63], v[62:63], v[68:69], v[70:71]
	s_nop 0
	v_rcp_f32_e32 v57, v57
	s_nop 0
	v_rcp_f32_e32 v56, v56
	v_lshlrev_b32_e32 v68, 16, v93
	v_and_b32_e32 v69, 0xffff0000, v93
	v_lshlrev_b32_e32 v70, 16, v97
	v_and_b32_e32 v71, 0xffff0000, v97
	v_pk_fma_f32 v[68:69], v[56:57], v[68:69], v[70:71]
	v_cvt_pk_bf16_f32 v56, v58, v59
	v_cvt_pk_bf16_f32 v57, v60, v61
	v_cvt_pk_bf16_f32 v58, v62, v63
	v_cvt_pk_bf16_f32 v59, v68, v69
	global_store_dwordx4 v[66:67], v[56:59], off
	s_nop 1
	v_exp_f32_e32 v56, v48
	v_mul_f32_e32 v48, 0xbfb8aa3b, v49
	v_exp_f32_e32 v57, v48
	v_mul_f32_e32 v48, 0xbfb8aa3b, v50
	v_mul_f32_e32 v49, 0xbfb8aa3b, v51
	v_pk_add_f32 v[50:51], v[52:53], 1.0 op_sel_hi:[1,0]
	v_exp_f32_e32 v48, v48
	v_exp_f32_e32 v49, v49
	v_rcp_f32_e32 v51, v51
	v_pk_add_f32 v[48:49], v[48:49], 1.0 op_sel_hi:[1,0]
	v_rcp_f32_e32 v50, v50
	s_waitcnt vmcnt(7)
	v_lshlrev_b32_e32 v52, 16, v86
	v_and_b32_e32 v53, 0xffff0000, v86
	v_lshlrev_b32_e32 v58, 16, v82
	v_and_b32_e32 v59, 0xffff0000, v82
	v_pk_fma_f32 v[50:51], v[50:51], v[52:53], v[58:59]
	v_pk_add_f32 v[52:53], v[54:55], 1.0 op_sel_hi:[1,0]
	s_nop 0
	s_nop 0
	v_rcp_f32_e32 v53, v53
	s_nop 0
	v_rcp_f32_e32 v52, v52
	v_lshlrev_b32_e32 v54, 16, v87
	v_and_b32_e32 v55, 0xffff0000, v87
	v_lshlrev_b32_e32 v58, 16, v83
	v_and_b32_e32 v59, 0xffff0000, v83
	v_pk_fma_f32 v[52:53], v[52:53], v[54:55], v[58:59]
	v_pk_add_f32 v[54:55], v[56:57], 1.0 op_sel_hi:[1,0]
	s_nop 0
	s_nop 0
	v_rcp_f32_e32 v55, v55
	s_nop 0
	v_rcp_f32_e32 v54, v54
	v_lshlrev_b32_e32 v56, 16, v88
	v_and_b32_e32 v57, 0xffff0000, v88
	v_lshlrev_b32_e32 v58, 16, v84
	v_and_b32_e32 v59, 0xffff0000, v84
	v_pk_fma_f32 v[54:55], v[54:55], v[56:57], v[58:59]
	s_nop 0
	v_rcp_f32_e32 v49, v49
	s_nop 0
	v_rcp_f32_e32 v48, v48
	v_lshlrev_b32_e32 v56, 16, v89
	v_and_b32_e32 v57, 0xffff0000, v89
	v_lshlrev_b32_e32 v58, 16, v85
	v_and_b32_e32 v59, 0xffff0000, v85
	v_pk_fma_f32 v[56:57], v[48:49], v[56:57], v[58:59]
	v_cvt_pk_bf16_f32 v48, v50, v51
	v_cvt_pk_bf16_f32 v49, v52, v53
	v_cvt_pk_bf16_f32 v50, v54, v55
	v_cvt_pk_bf16_f32 v51, v56, v57
	global_store_dwordx4 v[66:67], v[48:51], off offset:256
	v_mov_b32_e32 v66, 0
	s_and_b64 vcc, exec, s[42:43]
	v_add_u32_e32 v48, 0xa0, v206
	v_ashrrev_i32_e32 v49, 31, v48
	v_lshlrev_b64 v[50:51], 13, v[48:49]
	v_lshl_add_u64 v[50:51], v[204:205], 0, v[50:51]
	s_waitcnt vmcnt(4)
	v_mov_b64_e32 v[74:75], v[188:189]
	v_mov_b64_e32 v[76:77], v[190:191]
	v_lshlrev_b64 v[84:85], 11, v[48:49]
	v_lshl_add_u64 v[48:49], v[208:209], 0, v[84:85]
	s_cbranch_vccnz .LBB0_927
	global_load_dwordx4 v[78:81], v[48:49], off
